# P0 adaLN gemv: cond-vector staging with 18 loads in flight instead of a serialised load-per-trip loop
# baseline (speedup 1.0000x reference)
; __device__ __forceinline__ float fast_sigmoid(float x) { return __builtin_amdgcn_rcpf(1.0f + __builtin_amdgcn_exp2f(-x * LOG2E)); }
; template <bool SILU>
; __device__ __forceinline__ void gemv9_unit(const Ctx& X, const float* c0, int cstride, const float* c8, const float* W, int ldw, int j0, const float* bias, float* out, int ostride) {
;     ...
;     __syncthreads();
;     for (int i = X.tid; i < 9 * 1024; i += 512) { const int r = i >> 10, k = i & 1023; float v = r < 8 ? c0[(size_t)r * cstride + k] : c8[k]; if (SILU) v = v * fast_sigmoid(v); sc[i] = v; }
;     __syncthreads();
;     const int cgi = X.tid & 15, kg = X.tid >> 4;
;     const float* wp = W + (size_t)(kg * 32) * ldw + j0 + cgi * 4;
;     f32x4 a[9];
; #pragma unroll
;     for (int r = 0; r < 9; ++r) a[r] = (f32x4){0.f, 0.f, 0.f, 0.f};
; __global__ void __launch_bounds__(512, 2) fwd_megakernel(Args args) {
;     ...
;         for (int u = X.bx; u < 288; u += GW) { const int l = u / 144, j0 = (u % 144) * 64; gemv9_unit<true>(X, args.in[1], 1024, args.in[3], args.in[4] + (size_t)l * 1024 * 9216, 9216, j0, args.in[5] + (size_t)l * 9216, MOD + (size_t)l * 9 * 9216, 9216); }
.LBB0_36:
	s_barrier
	s_add_u32 s14, s38, 0x0
	s_addc_u32 s15, s39, 0
	global_load_dword v4, v3, s[14:15]
	global_load_dword v5, v3, s[14:15] offset:2048
	s_add_u32 s14, s38, 0x1000
	s_addc_u32 s15, s39, 0
	global_load_dword v6, v3, s[14:15]
	global_load_dword v7, v3, s[14:15] offset:2048
	s_add_u32 s14, s38, 0x2000
	s_addc_u32 s15, s39, 0
	global_load_dword v8, v3, s[14:15]
	global_load_dword v9, v3, s[14:15] offset:2048
	s_add_u32 s14, s38, 0x3000
	s_addc_u32 s15, s39, 0
	global_load_dword v10, v3, s[14:15]
	global_load_dword v11, v3, s[14:15] offset:2048
	s_add_u32 s14, s38, 0x4000
	s_addc_u32 s15, s39, 0
	global_load_dword v12, v3, s[14:15]
	global_load_dword v13, v3, s[14:15] offset:2048
	s_add_u32 s14, s38, 0x5000
	s_addc_u32 s15, s39, 0
	global_load_dword v14, v3, s[14:15]
	global_load_dword v15, v3, s[14:15] offset:2048
	s_add_u32 s14, s38, 0x6000
	s_addc_u32 s15, s39, 0
	global_load_dword v16, v3, s[14:15]
	global_load_dword v17, v3, s[14:15] offset:2048
	s_add_u32 s14, s38, 0x7000
	s_addc_u32 s15, s39, 0
	global_load_dword v18, v3, s[14:15]
	global_load_dword v19, v3, s[14:15] offset:2048
	s_mov_b64 s[14:15], s[42:43]
	global_load_dword v20, v3, s[14:15]
	global_load_dword v21, v3, s[14:15] offset:2048
	s_waitcnt vmcnt(17)
	v_mul_f32_e32 v22, 0xbfb8aa3b, v4
	s_waitcnt vmcnt(16)
	v_mul_f32_e32 v23, 0xbfb8aa3b, v5
	s_waitcnt vmcnt(15)
	v_mul_f32_e32 v24, 0xbfb8aa3b, v6
	s_waitcnt vmcnt(14)
	v_mul_f32_e32 v25, 0xbfb8aa3b, v7
	s_waitcnt vmcnt(13)
	v_mul_f32_e32 v26, 0xbfb8aa3b, v8
	s_waitcnt vmcnt(12)
	v_mul_f32_e32 v27, 0xbfb8aa3b, v9
	s_waitcnt vmcnt(11)
	v_mul_f32_e32 v28, 0xbfb8aa3b, v10
	s_waitcnt vmcnt(10)
	v_mul_f32_e32 v29, 0xbfb8aa3b, v11
	s_waitcnt vmcnt(9)
	v_mul_f32_e32 v30, 0xbfb8aa3b, v12
	s_waitcnt vmcnt(8)
	v_mul_f32_e32 v31, 0xbfb8aa3b, v13
	s_waitcnt vmcnt(7)
	v_mul_f32_e32 v32, 0xbfb8aa3b, v14
	s_waitcnt vmcnt(6)
	v_mul_f32_e32 v33, 0xbfb8aa3b, v15
	s_waitcnt vmcnt(5)
	v_mul_f32_e32 v34, 0xbfb8aa3b, v16
	s_waitcnt vmcnt(4)
	v_mul_f32_e32 v35, 0xbfb8aa3b, v17
	s_waitcnt vmcnt(3)
	v_mul_f32_e32 v36, 0xbfb8aa3b, v18
	s_waitcnt vmcnt(2)
	v_mul_f32_e32 v37, 0xbfb8aa3b, v19
	s_waitcnt vmcnt(1)
	v_mul_f32_e32 v38, 0xbfb8aa3b, v20
	s_waitcnt vmcnt(0)
	v_mul_f32_e32 v39, 0xbfb8aa3b, v21
	v_exp_f32_e32 v22, v22
	v_exp_f32_e32 v23, v23
	v_exp_f32_e32 v24, v24
	v_exp_f32_e32 v25, v25
	v_exp_f32_e32 v26, v26
	v_exp_f32_e32 v27, v27
	v_exp_f32_e32 v28, v28
	v_exp_f32_e32 v29, v29
	v_exp_f32_e32 v30, v30
	v_exp_f32_e32 v31, v31
	v_exp_f32_e32 v32, v32
	v_exp_f32_e32 v33, v33
	v_exp_f32_e32 v34, v34
	v_exp_f32_e32 v35, v35
	v_exp_f32_e32 v36, v36
	v_exp_f32_e32 v37, v37
	v_exp_f32_e32 v38, v38
	v_exp_f32_e32 v39, v39
	v_add_f32_e32 v22, 1.0, v22
	v_add_f32_e32 v23, 1.0, v23
	v_add_f32_e32 v24, 1.0, v24
	v_add_f32_e32 v25, 1.0, v25
	v_add_f32_e32 v26, 1.0, v26
	v_add_f32_e32 v27, 1.0, v27
	v_add_f32_e32 v28, 1.0, v28
	v_add_f32_e32 v29, 1.0, v29
	v_add_f32_e32 v30, 1.0, v30
	v_add_f32_e32 v31, 1.0, v31
	v_add_f32_e32 v32, 1.0, v32
	v_add_f32_e32 v33, 1.0, v33
	v_add_f32_e32 v34, 1.0, v34
	v_add_f32_e32 v35, 1.0, v35
	v_add_f32_e32 v36, 1.0, v36
	v_add_f32_e32 v37, 1.0, v37
	v_add_f32_e32 v38, 1.0, v38
	v_add_f32_e32 v39, 1.0, v39
	v_rcp_f32_e32 v22, v22
	v_rcp_f32_e32 v23, v23
	v_rcp_f32_e32 v24, v24
	v_rcp_f32_e32 v25, v25
	v_rcp_f32_e32 v26, v26
	v_rcp_f32_e32 v27, v27
	v_rcp_f32_e32 v28, v28
	v_rcp_f32_e32 v29, v29
	v_rcp_f32_e32 v30, v30
	v_rcp_f32_e32 v31, v31
	v_rcp_f32_e32 v32, v32
	v_rcp_f32_e32 v33, v33
	v_rcp_f32_e32 v34, v34
	v_rcp_f32_e32 v35, v35
	v_rcp_f32_e32 v36, v36
	v_rcp_f32_e32 v37, v37
	v_rcp_f32_e32 v38, v38
	v_rcp_f32_e32 v39, v39
	v_mul_f32_e32 v4, v4, v22
	v_mul_f32_e32 v5, v5, v23
	v_mul_f32_e32 v6, v6, v24
	v_mul_f32_e32 v7, v7, v25
	v_mul_f32_e32 v8, v8, v26
	v_mul_f32_e32 v9, v9, v27
	v_mul_f32_e32 v10, v10, v28
	v_mul_f32_e32 v11, v11, v29
	v_mul_f32_e32 v12, v12, v30
	v_mul_f32_e32 v13, v13, v31
	v_mul_f32_e32 v14, v14, v32
	v_mul_f32_e32 v15, v15, v33
	v_mul_f32_e32 v16, v16, v34
	v_mul_f32_e32 v17, v17, v35
	v_mul_f32_e32 v18, v18, v36
	v_mul_f32_e32 v19, v19, v37
	v_mul_f32_e32 v20, v20, v38
	v_mul_f32_e32 v21, v21, v39
	ds_write_b32 v3, v4
	ds_write_b32 v3, v5 offset:2048
	ds_write_b32 v3, v6 offset:4096
	ds_write_b32 v3, v7 offset:6144
	ds_write_b32 v3, v8 offset:8192
	ds_write_b32 v3, v9 offset:10240
	ds_write_b32 v3, v10 offset:12288
	ds_write_b32 v3, v11 offset:14336
	ds_write_b32 v3, v12 offset:16384
	ds_write_b32 v3, v13 offset:18432
	ds_write_b32 v3, v14 offset:20480
	ds_write_b32 v3, v15 offset:22528
	ds_write_b32 v3, v16 offset:24576
	ds_write_b32 v3, v17 offset:26624
	ds_write_b32 v3, v18 offset:28672
	ds_write_b32 v3, v19 offset:30720
	ds_write_b32 v3, v20 offset:32768
	ds_write_b32 v3, v21 offset:34816
	s_mul_hi_i32 s8, s22, 0x38e38e39
	s_lshr_b32 s9, s8, 31
	s_ashr_i32 s8, s8, 5
	s_add_i32 s23, s8, s9
	s_mul_i32 s8, s23, 0x90
	s_sub_i32 s8, s22, s8
	s_lshl_b32 s8, s8, 6
	s_ashr_i32 s9, s8, 31
	s_mul_i32 s16, s23, 0x2400000
	s_lshl_b64 s[14:15], s[8:9], 2
	s_mul_hi_i32 s17, s23, 0x2400000
	s_add_u32 s16, s16, s14
	s_addc_u32 s17, s17, s15
	v_mov_b32_e32 v4, 0
	v_lshl_add_u64 v[120:121], v[116:117], 0, s[16:17]
	s_mov_b64 s[16:17], 0
	v_mov_b32_e32 v114, v113
	v_mov_b32_e32 v5, v4
	v_mov_b32_e32 v6, v4
	v_mov_b32_e32 v7, v4
	v_mov_b32_e32 v8, v4
	v_mov_b32_e32 v9, v4
	v_mov_b32_e32 v10, v4
	v_mov_b32_e32 v11, v4
	v_mov_b32_e32 v12, v4
	v_mov_b32_e32 v13, v4
	v_mov_b32_e32 v14, v4
	v_mov_b32_e32 v15, v4
	v_mov_b32_e32 v16, v4
	v_mov_b32_e32 v17, v4
	v_mov_b32_e32 v18, v4
	v_mov_b32_e32 v19, v4
	v_mov_b32_e32 v20, v4
	v_mov_b32_e32 v21, v4
	v_mov_b32_e32 v22, v4
	v_mov_b32_e32 v23, v4
	v_mov_b32_e32 v24, v4
	v_mov_b32_e32 v25, v4
	v_mov_b32_e32 v26, v4
	v_mov_b32_e32 v27, v4
	v_mov_b32_e32 v28, v4
	v_mov_b32_e32 v29, v4
	v_mov_b32_e32 v30, v4
	v_mov_b32_e32 v31, v4
	v_mov_b32_e32 v32, v4
	v_mov_b32_e32 v33, v4
	v_mov_b32_e32 v34, v4
	v_mov_b32_e32 v35, v4
	v_mov_b32_e32 v36, v4
	v_mov_b32_e32 v37, v4
	v_mov_b32_e32 v38, v4
	v_mov_b32_e32 v39, v4
	s_waitcnt lgkmcnt(0)
	s_barrier
